# pad down-GEMM K-loop start by 16 bytes (code placement)
# speedup vs baseline: 1.0157x; 1.0042x over previous
; #define PG8_STAGE(bufoff, gbase, voff) do { _Pragma("unroll") for (int _i = 0; _i < 2; ++_i) \
;         __builtin_amdgcn_global_load_lds((const unsigned*)((const char*)(gbase) + (voff)[_i]), (PG8_LAS unsigned*)(lds + (bufoff) + ldsw + _i * 8192), 16, 0, 0); } while (0)
; #define PG8_LDA(dst, b, h) do { _Pragma("unroll") for (int m = 0; m < 4; ++m) _Pragma("unroll") for (int k = 0; k < 2; ++k) dst[m][k] = *(const PG8_LAS bf16x8*)(lds + PG8_SA(b, h) + aoff + m * 2048 + k * 1024); } while (0)
; #define PG8_LDB(dst, b, h) do { _Pragma("unroll") for (int n = 0; n < 2; ++n) _Pragma("unroll") for (int k = 0; k < 2; ++k) dst[n][k] = *(const PG8_LAS bf16x8*)(lds + PG8_SB(b, h) + boff + n * 2048 + k * 1024); } while (0)
; #define PG8_MMA(ai, bj, At, Bt) do { __builtin_amdgcn_s_setprio(1); _Pragma("unroll") for (int m = 0; m < 4; ++m) _Pragma("unroll") for (int n = 0; n < 2; ++n) _Pragma("unroll") for (int k = 0; k < 2; ++k) \
;         acc[ai][bj][m][n] = __builtin_amdgcn_mfma_f32_16x16x32_bf16(Bt[n][k], At[m][k], acc[ai][bj][m][n], 0, 0, 0); __builtin_amdgcn_s_setprio(0); } while (0)
; #define PG8_WAIT_V(n) asm volatile("s_waitcnt vmcnt(" #n ")" ::: "memory")
; template <class Epi, class Sched, bool ALIGN_EPI = true>
; __device__ __forceinline__ void gemm_phase(PG8_LAS unsigned char* lds, const Gemm g, const Sched& S, const Epi& E, const int tid) {
;     ...
;     f32x4 acc[2][2][4][2];
; #pragma unroll
;     for (int a = 0; a < 2; ++a)
; #pragma unroll
;         for (int b = 0; b < 2; ++b)
; #pragma unroll
;             for (int m = 0; m < 4; ++m)
; #pragma unroll
;                 for (int n = 0; n < 2; ++n) acc[a][b][m][n] = (f32x4){0.f, 0.f, 0.f, 0.f};
;     ...
;         const int nt = cur.nkt;
;         for (int t = 0; t < nt; t += 2) {
;             const bool last = (t == nt - 2);
;             const char* a1 = cA + (size_t)(t + 1) * kstep;
;             const char* a2 = last ? nA : cA + (size_t)(t + 2) * kstep; const char* b2 = last ? nB : cB + (size_t)(t + 2) * kstep;
;             const char* a3 = a2 + kstep; const char* b3 = b2 + kstep;
;             if (last && has_next) S.a_ready(nxt);
;             PG8_LDB(B0, 0, 0); PG8_LDB(B1, 0, 1); PG8_SCHED; PG8_LDA(At, 0, 0); PG8_STAGE(PG8_SA(1, 1), a1 + hstepA, voffA);
;             PG8_WAIT_V(8); PG8_WAIT_L(0); PG8_BAR; PG8_MMA(0, 0, At, B0); PG8_MMA(0, 1, At, B1); PG8_BAR; PG8_SCHED;
.LBB0_1413:
	s_add_i32 s45, s67, -2
	s_add_u32 s68, s12, 0x100
	v_mov_b32_e32 v4, 0
	s_addc_u32 s69, s13, 0
	s_mov_b32 s12, 0
	v_mov_b32_e32 v5, v4
	v_mov_b32_e32 v6, v4
	v_mov_b32_e32 v7, v4
	v_mov_b32_e32 v8, v4
	v_mov_b32_e32 v9, v4
	v_mov_b32_e32 v10, v4
	v_mov_b32_e32 v11, v4
	v_mov_b32_e32 v20, v4
	v_mov_b32_e32 v21, v4
	v_mov_b32_e32 v22, v4
	v_mov_b32_e32 v23, v4
	v_mov_b32_e32 v24, v4
	v_mov_b32_e32 v25, v4
	v_mov_b32_e32 v26, v4
	v_mov_b32_e32 v27, v4
	v_mov_b32_e32 v36, v4
	v_mov_b32_e32 v37, v4
	v_mov_b32_e32 v38, v4
	v_mov_b32_e32 v39, v4
	v_mov_b32_e32 v40, v4
	v_mov_b32_e32 v41, v4
	v_mov_b32_e32 v42, v4
	v_mov_b32_e32 v43, v4
	v_mov_b32_e32 v52, v4
	v_mov_b32_e32 v53, v4
	v_mov_b32_e32 v54, v4
	v_mov_b32_e32 v55, v4
	s_waitcnt vmcnt(0)
	v_mov_b32_e32 v64, v4
	v_mov_b32_e32 v65, v4
	v_mov_b32_e32 v66, v4
	v_mov_b32_e32 v67, v4
	v_mov_b32_e32 v12, v4
	v_mov_b32_e32 v13, v4
	v_mov_b32_e32 v14, v4
	v_mov_b32_e32 v15, v4
	v_mov_b32_e32 v16, v4
	v_mov_b32_e32 v17, v4
	v_mov_b32_e32 v18, v4
	v_mov_b32_e32 v19, v4
	v_mov_b32_e32 v28, v4
	v_mov_b32_e32 v29, v4
	v_mov_b32_e32 v30, v4
	v_mov_b32_e32 v31, v4
	v_mov_b32_e32 v32, v4
	v_mov_b32_e32 v33, v4
	v_mov_b32_e32 v34, v4
	v_mov_b32_e32 v35, v4
	v_mov_b32_e32 v44, v4
	v_mov_b32_e32 v45, v4
	v_mov_b32_e32 v46, v4
	v_mov_b32_e32 v47, v4
	v_mov_b32_e32 v48, v4
	v_mov_b32_e32 v49, v4
	v_mov_b32_e32 v50, v4
	v_mov_b32_e32 v51, v4
	v_mov_b32_e32 v76, v4
	v_mov_b32_e32 v77, v4
	v_mov_b32_e32 v78, v4
	v_mov_b32_e32 v79, v4
	v_mov_b32_e32 v80, v4
	v_mov_b32_e32 v81, v4
	v_mov_b32_e32 v82, v4
	v_mov_b32_e32 v83, v4
	v_mov_b32_e32 v84, v4
	v_mov_b32_e32 v85, v4
	v_mov_b32_e32 v86, v4
	v_mov_b32_e32 v87, v4
	v_mov_b32_e32 v88, v4
	v_mov_b32_e32 v89, v4
	v_mov_b32_e32 v90, v4
	v_mov_b32_e32 v91, v4
	v_mov_b32_e32 v108, v4
	v_mov_b32_e32 v109, v4
	v_mov_b32_e32 v110, v4
	v_mov_b32_e32 v111, v4
	v_mov_b32_e32 v112, v4
	v_mov_b32_e32 v113, v4
	v_mov_b32_e32 v114, v4
	v_mov_b32_e32 v115, v4
	v_mov_b32_e32 v132, v4
	v_mov_b32_e32 v133, v4
	v_mov_b32_e32 v134, v4
	v_mov_b32_e32 v135, v4
	v_mov_b32_e32 v136, v4
	v_mov_b32_e32 v137, v4
	v_mov_b32_e32 v138, v4
	v_mov_b32_e32 v139, v4
	v_mov_b32_e32 v164, v4
	v_mov_b32_e32 v165, v4
	v_mov_b32_e32 v166, v4
	v_mov_b32_e32 v167, v4
	v_mov_b32_e32 v168, v4
	v_mov_b32_e32 v169, v4
	v_mov_b32_e32 v170, v4
	v_mov_b32_e32 v171, v4
	v_mov_b32_e32 v96, v4
	v_mov_b32_e32 v97, v4
	v_mov_b32_e32 v98, v4
	v_mov_b32_e32 v99, v4
	v_mov_b32_e32 v100, v4
	v_mov_b32_e32 v101, v4
	v_mov_b32_e32 v102, v4
	v_mov_b32_e32 v103, v4
	v_mov_b32_e32 v120, v4
	v_mov_b32_e32 v121, v4
	v_mov_b32_e32 v122, v4
	v_mov_b32_e32 v123, v4
	v_mov_b32_e32 v124, v4
	v_mov_b32_e32 v125, v4
	v_mov_b32_e32 v126, v4
	v_mov_b32_e32 v127, v4
	v_mov_b32_e32 v144, v4
	v_mov_b32_e32 v145, v4
	v_mov_b32_e32 v146, v4
	v_mov_b32_e32 v147, v4
	v_mov_b32_e32 v148, v4
	v_mov_b32_e32 v149, v4
	v_mov_b32_e32 v150, v4
	v_mov_b32_e32 v151, v4
	v_mov_b32_e32 v176, v4
	v_mov_b32_e32 v177, v4
	v_mov_b32_e32 v178, v4
	v_mov_b32_e32 v179, v4
	v_mov_b32_e32 v180, v4
	v_mov_b32_e32 v181, v4
	v_mov_b32_e32 v182, v4
	v_mov_b32_e32 v183, v4
	s_nop 0
	s_nop 0
	s_nop 0
	s_nop 0
.LBB0_1414:
	s_add_i32 s70, s12, 2
	s_add_u32 s10, s0, 0x100
	s_addc_u32 s11, s1, 0
	s_add_i32 s15, 0, 0x10000
	s_cmp_eq_u32 s45, s12
	s_cselect_b32 s23, s47, s11
	s_cselect_b32 s22, s46, s10
	s_cselect_b32 s13, s49, s69
	s_cselect_b32 s12, s48, s68
	s_add_i32 s16, 0, 0x14000
	v_add_u32_e32 v72, s15, v251
	v_add_u32_e32 v128, s16, v251
	ds_read_b128 v[56:59], v72
	ds_read_b128 v[60:63], v72 offset:1024
	ds_read_b128 v[68:71], v72 offset:2048
	ds_read_b128 v[72:75], v72 offset:3072
	ds_read_b128 v[92:95], v128
	ds_read_b128 v[104:107], v128 offset:1024
	ds_read_b128 v[116:119], v128 offset:2048
	ds_read_b128 v[128:131], v128 offset:3072
	v_lshl_add_u64 v[196:197], s[0:1], 0, v[216:217]
	s_add_i32 m0, s52, 0xc000
	ds_read_b128 v[140:143], v252
	ds_read_b128 v[152:155], v252 offset:1024
	ds_read_b128 v[156:159], v252 offset:2048
	ds_read_b128 v[160:163], v252 offset:3072
	ds_read_b128 v[172:175], v252 offset:4096
	ds_read_b128 v[184:187], v252 offset:5120
	ds_read_b128 v[188:191], v252 offset:6144
	ds_read_b128 v[192:195], v252 offset:7168
	global_load_lds_dwordx4 v[196:197], off
	v_lshl_add_u64 v[196:197], s[0:1], 0, v[218:219]
	s_add_i32 m0, s52, 0xe000
	s_nop 0
	global_load_lds_dwordx4 v[196:197], off
	s_waitcnt vmcnt(8)
	s_waitcnt lgkmcnt(0)
	s_barrier
	s_waitcnt lgkmcnt(0)
	v_mfma_f32_16x16x32_bf16 v[180:183], v[56:59], v[140:143], v[180:183]
	v_mfma_f32_16x16x32_bf16 v[180:183], v[60:63], v[152:155], v[180:183]
	v_mfma_f32_16x16x32_bf16 v[176:179], v[68:71], v[140:143], v[176:179]
	v_mfma_f32_16x16x32_bf16 v[176:179], v[72:75], v[152:155], v[176:179]
	v_mfma_f32_16x16x32_bf16 v[148:151], v[56:59], v[156:159], v[148:151]
	v_mfma_f32_16x16x32_bf16 v[148:151], v[60:63], v[160:163], v[148:151]
	v_mfma_f32_16x16x32_bf16 v[144:147], v[68:71], v[156:159], v[144:147]
	v_mfma_f32_16x16x32_bf16 v[144:147], v[72:75], v[160:163], v[144:147]
	v_mfma_f32_16x16x32_bf16 v[124:127], v[56:59], v[172:175], v[124:127]
	v_mfma_f32_16x16x32_bf16 v[124:127], v[60:63], v[184:187], v[124:127]
	v_mfma_f32_16x16x32_bf16 v[120:123], v[68:71], v[172:175], v[120:123]
	v_mfma_f32_16x16x32_bf16 v[120:123], v[72:75], v[184:187], v[120:123]
	v_mfma_f32_16x16x32_bf16 v[100:103], v[56:59], v[188:191], v[100:103]
	v_mfma_f32_16x16x32_bf16 v[100:103], v[60:63], v[192:195], v[100:103]
	v_mfma_f32_16x16x32_bf16 v[96:99], v[68:71], v[188:191], v[96:99]
	v_mfma_f32_16x16x32_bf16 v[96:99], v[72:75], v[192:195], v[96:99]
	v_mfma_f32_16x16x32_bf16 v[168:171], v[92:95], v[140:143], v[168:171]
	v_mfma_f32_16x16x32_bf16 v[136:139], v[92:95], v[156:159], v[136:139]
	v_mfma_f32_16x16x32_bf16 v[132:135], v[116:119], v[156:159], v[132:135]
	v_mfma_f32_16x16x32_bf16 v[112:115], v[92:95], v[172:175], v[112:115]
	v_mfma_f32_16x16x32_bf16 v[108:111], v[116:119], v[172:175], v[108:111]
	v_mfma_f32_16x16x32_bf16 v[88:91], v[92:95], v[188:191], v[88:91]
	v_mfma_f32_16x16x32_bf16 v[84:87], v[116:119], v[188:191], v[84:87]
	v_mfma_f32_16x16x32_bf16 v[168:171], v[104:107], v[152:155], v[168:171]
	v_mfma_f32_16x16x32_bf16 v[140:143], v[116:119], v[140:143], v[164:167]
	v_mfma_f32_16x16x32_bf16 v[136:139], v[104:107], v[160:163], v[136:139]
	v_mfma_f32_16x16x32_bf16 v[132:135], v[128:131], v[160:163], v[132:135]
	v_mfma_f32_16x16x32_bf16 v[112:115], v[104:107], v[184:187], v[112:115]
	v_mfma_f32_16x16x32_bf16 v[108:111], v[128:131], v[184:187], v[108:111]
	v_mfma_f32_16x16x32_bf16 v[88:91], v[104:107], v[192:195], v[88:91]
	v_mfma_f32_16x16x32_bf16 v[84:87], v[128:131], v[192:195], v[84:87]
	v_mfma_f32_16x16x32_bf16 v[140:143], v[128:131], v[152:155], v[140:143]
	s_barrier
; #define PG8_STAGE(bufoff, gbase, voff) do { _Pragma("unroll") for (int _i = 0; _i < 2; ++_i) \
;         __builtin_amdgcn_global_load_lds((const unsigned*)((const char*)(gbase) + (voff)[_i]), (PG8_LAS unsigned*)(lds + (bufoff) + ldsw + _i * 8192), 16, 0, 0); } while (0)
; #define PG8_LDA(dst, b, h) do { _Pragma("unroll") for (int m = 0; m < 4; ++m) _Pragma("unroll") for (int k = 0; k < 2; ++k) dst[m][k] = *(const PG8_LAS bf16x8*)(lds + PG8_SA(b, h) + aoff + m * 2048 + k * 1024); } while (0)
; #define PG8_LDB(dst, b, h) do { _Pragma("unroll") for (int n = 0; n < 2; ++n) _Pragma("unroll") for (int k = 0; k < 2; ++k) dst[n][k] = *(const PG8_LAS bf16x8*)(lds + PG8_SB(b, h) + boff + n * 2048 + k * 1024); } while (0)
; #define PG8_MMA(ai, bj, At, Bt) do { __builtin_amdgcn_s_setprio(1); _Pragma("unroll") for (int m = 0; m < 4; ++m) _Pragma("unroll") for (int n = 0; n < 2; ++n) _Pragma("unroll") for (int k = 0; k < 2; ++k) \
;         acc[ai][bj][m][n] = __builtin_amdgcn_mfma_f32_16x16x32_bf16(Bt[n][k], At[m][k], acc[ai][bj][m][n], 0, 0, 0); __builtin_amdgcn_s_setprio(0); } while (0)
; #define PG8_WAIT_V(n) asm volatile("s_waitcnt vmcnt(" #n ")" ::: "memory")
; #define PG8_WAIT_L(n) asm volatile("s_waitcnt lgkmcnt(" #n ")" ::: "memory")
; #define PG8_BAR __builtin_amdgcn_s_barrier()
; #define PG8_SCHED __builtin_amdgcn_sched_barrier(0)
; template <class Epi, class Sched, bool ALIGN_EPI = true>
; __device__ __forceinline__ void gemm_phase(PG8_LAS unsigned char* lds, const Gemm g, const Sched& S, const Epi& E, const int tid) {
;     ...
;             PG8_LDA(At, 0, 1); PG8_STAGE(PG8_SB(0, 0), b2, voffB); PG8_STAGE(PG8_SB(0, 1), b2 + hstepB, voffB); PG8_STAGE(PG8_SA(0, 0), a2, voffA);
;             PG8_WAIT_V(8); PG8_WAIT_L(0); PG8_BAR; PG8_MMA(1, 0, At, B0); PG8_MMA(1, 1, At, B1); PG8_BAR; PG8_SCHED;
;             PG8_LDB(B0, 1, 0); PG8_LDB(B1, 1, 1); PG8_SCHED; PG8_LDA(At, 1, 0); PG8_STAGE(PG8_SA(0, 1), a2 + hstepA, voffA);
	s_add_i32 s0, s15, s51
	v_lshl_add_u64 v[200:201], s[12:13], 0, v[2:3]
	s_mov_b32 m0, s0
	ds_read_b128 v[152:155], v252 offset:16384
	ds_read_b128 v[156:159], v252 offset:17408
	ds_read_b128 v[160:163], v252 offset:18432
	ds_read_b128 v[164:167], v252 offset:19456
	ds_read_b128 v[172:175], v252 offset:20480
	ds_read_b128 v[184:187], v252 offset:21504
	ds_read_b128 v[188:191], v252 offset:22528
	ds_read_b128 v[192:195], v252 offset:23552
	global_load_lds_dwordx4 v[200:201], off
	s_add_i32 m0, s0, 0x2000
	s_add_u32 s0, s12, 0x168000
	v_lshl_add_u64 v[202:203], s[12:13], 0, v[214:215]
	s_addc_u32 s1, s13, 0
	s_add_i32 s15, s16, s51
	global_load_lds_dwordx4 v[202:203], off
	v_lshl_add_u64 v[196:197], s[0:1], 0, v[2:3]
	s_mov_b32 m0, s15
	v_lshl_add_u64 v[204:205], s[22:23], 0, v[210:211]
	global_load_lds_dwordx4 v[196:197], off
	v_lshl_add_u64 v[196:197], s[0:1], 0, v[214:215]
	s_add_i32 m0, s15, 0x2000
	v_lshl_add_u64 v[206:207], s[22:23], 0, v[212:213]
	global_load_lds_dwordx4 v[196:197], off
	s_mov_b32 m0, s52
	s_nop 0
	global_load_lds_dwordx4 v[204:205], off
	s_mov_b32 m0, s53
	s_nop 0
	global_load_lds_dwordx4 v[206:207], off
	s_waitcnt vmcnt(8)
	s_waitcnt lgkmcnt(0)
	s_barrier
	s_waitcnt lgkmcnt(0)
	v_mfma_f32_16x16x32_bf16 v[80:83], v[56:59], v[152:155], v[80:83]
	v_mfma_f32_16x16x32_bf16 v[80:83], v[60:63], v[156:159], v[80:83]
	v_mfma_f32_16x16x32_bf16 v[76:79], v[68:71], v[152:155], v[76:79]
	v_mfma_f32_16x16x32_bf16 v[76:79], v[72:75], v[156:159], v[76:79]
	v_mfma_f32_16x16x32_bf16 v[48:51], v[56:59], v[160:163], v[48:51]
	v_mfma_f32_16x16x32_bf16 v[48:51], v[60:63], v[164:167], v[48:51]
	v_mfma_f32_16x16x32_bf16 v[44:47], v[68:71], v[160:163], v[44:47]
	v_mfma_f32_16x16x32_bf16 v[44:47], v[72:75], v[164:167], v[44:47]
	v_mfma_f32_16x16x32_bf16 v[32:35], v[56:59], v[172:175], v[32:35]
	v_mfma_f32_16x16x32_bf16 v[32:35], v[60:63], v[184:187], v[32:35]
	v_mfma_f32_16x16x32_bf16 v[28:31], v[68:71], v[172:175], v[28:31]
	v_mfma_f32_16x16x32_bf16 v[28:31], v[72:75], v[184:187], v[28:31]
	v_mfma_f32_16x16x32_bf16 v[16:19], v[56:59], v[188:191], v[16:19]
	v_mfma_f32_16x16x32_bf16 v[16:19], v[60:63], v[192:195], v[16:19]
	v_mfma_f32_16x16x32_bf16 v[12:15], v[68:71], v[188:191], v[12:15]
	v_mfma_f32_16x16x32_bf16 v[12:15], v[72:75], v[192:195], v[12:15]
	v_mfma_f32_16x16x32_bf16 v[52:55], v[116:119], v[152:155], v[52:55]
	v_mfma_f32_16x16x32_bf16 v[40:43], v[92:95], v[160:163], v[40:43]
	v_mfma_f32_16x16x32_bf16 v[36:39], v[116:119], v[160:163], v[36:39]
	v_mfma_f32_16x16x32_bf16 v[24:27], v[92:95], v[172:175], v[24:27]
	v_mfma_f32_16x16x32_bf16 v[20:23], v[116:119], v[172:175], v[20:23]
	v_mfma_f32_16x16x32_bf16 v[8:11], v[92:95], v[188:191], v[8:11]
	v_mfma_f32_16x16x32_bf16 v[4:7], v[116:119], v[188:191], v[4:7]
	v_mfma_f32_16x16x32_bf16 v[56:59], v[92:95], v[152:155], v[64:67]
	v_mfma_f32_16x16x32_bf16 v[52:55], v[128:131], v[156:159], v[52:55]
	v_mfma_f32_16x16x32_bf16 v[40:43], v[104:107], v[164:167], v[40:43]
	v_mfma_f32_16x16x32_bf16 v[36:39], v[128:131], v[164:167], v[36:39]
	v_mfma_f32_16x16x32_bf16 v[24:27], v[104:107], v[184:187], v[24:27]
	v_mfma_f32_16x16x32_bf16 v[20:23], v[128:131], v[184:187], v[20:23]
	v_mfma_f32_16x16x32_bf16 v[8:11], v[104:107], v[192:195], v[8:11]
	v_mfma_f32_16x16x32_bf16 v[4:7], v[128:131], v[192:195], v[4:7]
	v_mfma_f32_16x16x32_bf16 v[56:59], v[104:107], v[156:159], v[56:59]
	s_barrier
	s_add_i32 s15, 0, 0x18000
	s_add_i32 s16, 0, 0x1c000
	v_add_u32_e32 v72, s15, v251
	v_add_u32_e32 v128, s16, v251
	ds_read_b128 v[60:63], v72
	ds_read_b128 v[64:67], v72 offset:1024
	ds_read_b128 v[68:71], v72 offset:2048
	ds_read_b128 v[72:75], v72 offset:3072
	ds_read_b128 v[92:95], v128
	ds_read_b128 v[104:107], v128 offset:1024
	ds_read_b128 v[116:119], v128 offset:2048
	ds_read_b128 v[128:131], v128 offset:3072
	s_add_u32 s0, s22, 0x168000
	s_addc_u32 s1, s23, 0
	s_mov_b32 m0, s54
	v_lshl_add_u64 v[164:165], s[0:1], 0, v[210:211]
	ds_read_b128 v[152:155], v252 offset:32768
	ds_read_b128 v[156:159], v252 offset:33792
	ds_read_b128 v[160:163], v252 offset:34816
	ds_read_b128 v[172:175], v252 offset:35840
	ds_read_b128 v[184:187], v252 offset:36864
	ds_read_b128 v[188:191], v252 offset:37888
	ds_read_b128 v[192:195], v252 offset:38912
	ds_read_b128 v[196:199], v252 offset:39936
	global_load_lds_dwordx4 v[164:165], off
	v_lshl_add_u64 v[164:165], s[0:1], 0, v[212:213]
	s_mov_b32 m0, s55
	s_nop 0
	global_load_lds_dwordx4 v[164:165], off
	s_waitcnt vmcnt(8)
	s_waitcnt lgkmcnt(0)
	s_barrier
; #define PG8_STAGE(bufoff, gbase, voff) do { _Pragma("unroll") for (int _i = 0; _i < 2; ++_i) \
;         __builtin_amdgcn_global_load_lds((const unsigned*)((const char*)(gbase) + (voff)[_i]), (PG8_LAS unsigned*)(lds + (bufoff) + ldsw + _i * 8192), 16, 0, 0); } while (0)
; #define PG8_LDA(dst, b, h) do { _Pragma("unroll") for (int m = 0; m < 4; ++m) _Pragma("unroll") for (int k = 0; k < 2; ++k) dst[m][k] = *(const PG8_LAS bf16x8*)(lds + PG8_SA(b, h) + aoff + m * 2048 + k * 1024); } while (0)
; #define PG8_MMA(ai, bj, At, Bt) do { __builtin_amdgcn_s_setprio(1); _Pragma("unroll") for (int m = 0; m < 4; ++m) _Pragma("unroll") for (int n = 0; n < 2; ++n) _Pragma("unroll") for (int k = 0; k < 2; ++k) \
;         acc[ai][bj][m][n] = __builtin_amdgcn_mfma_f32_16x16x32_bf16(Bt[n][k], At[m][k], acc[ai][bj][m][n], 0, 0, 0); __builtin_amdgcn_s_setprio(0); } while (0)
; #define PG8_WAIT_V(n) asm volatile("s_waitcnt vmcnt(" #n ")" ::: "memory")
; #define PG8_WAIT_L(n) asm volatile("s_waitcnt lgkmcnt(" #n ")" ::: "memory")
; #define PG8_BAR __builtin_amdgcn_s_barrier()
; #define PG8_SCHED __builtin_amdgcn_sched_barrier(0)
; template <class Epi, class Sched, bool ALIGN_EPI = true>
; __device__ __forceinline__ void gemm_phase(PG8_LAS unsigned char* lds, const Gemm g, const Sched& S, const Epi& E, const int tid) {
;     ...
;             PG8_WAIT_V(8); PG8_WAIT_L(0); PG8_BAR; PG8_MMA(0, 0, At, B0); PG8_MMA(0, 1, At, B1); PG8_BAR; PG8_SCHED;
;             PG8_LDA(At, 1, 1); PG8_STAGE(PG8_SB(1, 0), b3, voffB); PG8_STAGE(PG8_SB(1, 1), b3 + hstepB, voffB); PG8_STAGE(PG8_SA(1, 0), a3, voffA);
;             PG8_WAIT_V(8); PG8_WAIT_L(0); PG8_BAR; PG8_MMA(1, 0, At, B0); PG8_MMA(1, 1, At, B1); PG8_BAR; PG8_SCHED;
;         }
;         if constexpr (ALIGN_EPI) { if (wr == 0) PG8_BAR; }
	s_waitcnt lgkmcnt(0)
	v_mfma_f32_16x16x32_bf16 v[164:167], v[60:63], v[152:155], v[180:183]
	v_mfma_f32_16x16x32_bf16 v[180:183], v[64:67], v[156:159], v[164:167]
	v_mfma_f32_16x16x32_bf16 v[164:167], v[68:71], v[152:155], v[176:179]
	v_mfma_f32_16x16x32_bf16 v[148:151], v[60:63], v[160:163], v[148:151]
	v_mfma_f32_16x16x32_bf16 v[144:147], v[68:71], v[160:163], v[144:147]
	v_mfma_f32_16x16x32_bf16 v[124:127], v[60:63], v[184:187], v[124:127]
	v_mfma_f32_16x16x32_bf16 v[120:123], v[68:71], v[184:187], v[120:123]
	v_mfma_f32_16x16x32_bf16 v[100:103], v[60:63], v[192:195], v[100:103]
	v_mfma_f32_16x16x32_bf16 v[96:99], v[68:71], v[192:195], v[96:99]
	v_mfma_f32_16x16x32_bf16 v[176:179], v[72:75], v[156:159], v[164:167]
	v_mfma_f32_16x16x32_bf16 v[148:151], v[64:67], v[172:175], v[148:151]
	v_mfma_f32_16x16x32_bf16 v[144:147], v[72:75], v[172:175], v[144:147]
	v_mfma_f32_16x16x32_bf16 v[124:127], v[64:67], v[188:191], v[124:127]
	v_mfma_f32_16x16x32_bf16 v[120:123], v[72:75], v[188:191], v[120:123]
	v_mfma_f32_16x16x32_bf16 v[100:103], v[64:67], v[196:199], v[100:103]
	v_mfma_f32_16x16x32_bf16 v[96:99], v[72:75], v[196:199], v[96:99]
	v_mfma_f32_16x16x32_bf16 v[164:167], v[92:95], v[152:155], v[168:171]
	v_mfma_f32_16x16x32_bf16 v[140:143], v[116:119], v[152:155], v[140:143]
	v_mfma_f32_16x16x32_bf16 v[136:139], v[92:95], v[160:163], v[136:139]
	v_mfma_f32_16x16x32_bf16 v[132:135], v[116:119], v[160:163], v[132:135]
	v_mfma_f32_16x16x32_bf16 v[112:115], v[92:95], v[184:187], v[112:115]
	v_mfma_f32_16x16x32_bf16 v[108:111], v[116:119], v[184:187], v[108:111]
	v_mfma_f32_16x16x32_bf16 v[88:91], v[92:95], v[192:195], v[88:91]
	v_mfma_f32_16x16x32_bf16 v[84:87], v[116:119], v[192:195], v[84:87]
	v_mfma_f32_16x16x32_bf16 v[168:171], v[104:107], v[156:159], v[164:167]
	v_mfma_f32_16x16x32_bf16 v[164:167], v[128:131], v[156:159], v[140:143]
	v_mfma_f32_16x16x32_bf16 v[136:139], v[104:107], v[172:175], v[136:139]
	v_mfma_f32_16x16x32_bf16 v[132:135], v[128:131], v[172:175], v[132:135]
	v_mfma_f32_16x16x32_bf16 v[112:115], v[104:107], v[188:191], v[112:115]
	v_mfma_f32_16x16x32_bf16 v[108:111], v[128:131], v[188:191], v[108:111]
	v_mfma_f32_16x16x32_bf16 v[88:91], v[104:107], v[196:199], v[88:91]
	v_mfma_f32_16x16x32_bf16 v[84:87], v[128:131], v[196:199], v[84:87]
	s_barrier
	s_add_i32 s0, s15, s51
	v_lshl_add_u64 v[196:197], v[200:201], 0, s[36:37]
	s_mov_b32 m0, s0
	ds_read_b128 v[140:143], v252 offset:49152
	ds_read_b128 v[152:155], v252 offset:50176
	ds_read_b128 v[156:159], v252 offset:51200
	ds_read_b128 v[160:163], v252 offset:52224
	ds_read_b128 v[172:175], v252 offset:53248
	ds_read_b128 v[184:187], v252 offset:54272
	ds_read_b128 v[188:191], v252 offset:55296
	ds_read_b128 v[192:195], v252 offset:56320
	global_load_lds_dwordx4 v[196:197], off
	s_add_i32 m0, s0, 0x2000
	s_add_u32 s0, s12, 0x168080
	v_lshl_add_u64 v[196:197], v[202:203], 0, s[36:37]
	s_addc_u32 s1, s13, 0
	s_add_i32 s12, s16, s51
	global_load_lds_dwordx4 v[196:197], off
	v_lshl_add_u64 v[196:197], s[0:1], 0, v[2:3]
	s_mov_b32 m0, s12
	s_nop 0
	global_load_lds_dwordx4 v[196:197], off
	v_lshl_add_u64 v[196:197], s[0:1], 0, v[214:215]
	s_add_i32 m0, s12, 0x2000
	s_nop 0
	global_load_lds_dwordx4 v[196:197], off
	v_lshl_add_u64 v[196:197], v[204:205], 0, s[36:37]
	s_mov_b32 m0, s58
	s_nop 0
	global_load_lds_dwordx4 v[196:197], off
	v_lshl_add_u64 v[196:197], v[206:207], 0, s[36:37]
	s_mov_b32 m0, s59
	s_nop 0
	global_load_lds_dwordx4 v[196:197], off
	s_waitcnt vmcnt(8)
	s_waitcnt lgkmcnt(0)
	s_barrier
	s_waitcnt lgkmcnt(0)
	v_mfma_f32_16x16x32_bf16 v[80:83], v[60:63], v[140:143], v[80:83]
	v_mfma_f32_16x16x32_bf16 v[80:83], v[64:67], v[152:155], v[80:83]
	v_mfma_f32_16x16x32_bf16 v[76:79], v[68:71], v[140:143], v[76:79]
	v_mfma_f32_16x16x32_bf16 v[76:79], v[72:75], v[152:155], v[76:79]
	v_mfma_f32_16x16x32_bf16 v[48:51], v[60:63], v[156:159], v[48:51]
	v_mfma_f32_16x16x32_bf16 v[48:51], v[64:67], v[160:163], v[48:51]
	v_mfma_f32_16x16x32_bf16 v[44:47], v[68:71], v[156:159], v[44:47]
	v_mfma_f32_16x16x32_bf16 v[44:47], v[72:75], v[160:163], v[44:47]
	v_mfma_f32_16x16x32_bf16 v[32:35], v[60:63], v[172:175], v[32:35]
	v_mfma_f32_16x16x32_bf16 v[32:35], v[64:67], v[184:187], v[32:35]
	v_mfma_f32_16x16x32_bf16 v[28:31], v[68:71], v[172:175], v[28:31]
	v_mfma_f32_16x16x32_bf16 v[28:31], v[72:75], v[184:187], v[28:31]
	v_mfma_f32_16x16x32_bf16 v[16:19], v[60:63], v[188:191], v[16:19]
	v_mfma_f32_16x16x32_bf16 v[16:19], v[64:67], v[192:195], v[16:19]
	v_mfma_f32_16x16x32_bf16 v[12:15], v[68:71], v[188:191], v[12:15]
	v_mfma_f32_16x16x32_bf16 v[12:15], v[72:75], v[192:195], v[12:15]
	v_mfma_f32_16x16x32_bf16 v[56:59], v[92:95], v[140:143], v[56:59]
	v_mfma_f32_16x16x32_bf16 v[52:55], v[116:119], v[140:143], v[52:55]
	v_mfma_f32_16x16x32_bf16 v[40:43], v[92:95], v[156:159], v[40:43]
	v_mfma_f32_16x16x32_bf16 v[36:39], v[116:119], v[156:159], v[36:39]
	v_mfma_f32_16x16x32_bf16 v[24:27], v[92:95], v[172:175], v[24:27]
	v_mfma_f32_16x16x32_bf16 v[20:23], v[116:119], v[172:175], v[20:23]
	v_mfma_f32_16x16x32_bf16 v[8:11], v[92:95], v[188:191], v[8:11]
	v_mfma_f32_16x16x32_bf16 v[4:7], v[116:119], v[188:191], v[4:7]
	v_mfma_f32_16x16x32_bf16 v[64:67], v[104:107], v[152:155], v[56:59]
	v_mfma_f32_16x16x32_bf16 v[52:55], v[128:131], v[152:155], v[52:55]
	v_mfma_f32_16x16x32_bf16 v[40:43], v[104:107], v[160:163], v[40:43]
	v_mfma_f32_16x16x32_bf16 v[36:39], v[128:131], v[160:163], v[36:39]
	v_mfma_f32_16x16x32_bf16 v[24:27], v[104:107], v[184:187], v[24:27]
	v_mfma_f32_16x16x32_bf16 v[20:23], v[128:131], v[184:187], v[20:23]
	v_mfma_f32_16x16x32_bf16 v[8:11], v[104:107], v[192:195], v[8:11]
	v_mfma_f32_16x16x32_bf16 v[4:7], v[128:131], v[192:195], v[4:7]
	s_barrier
	s_add_u32 s68, s68, 0x100
	s_addc_u32 s69, s69, 0
	s_cmp_ge_i32 s70, s67
	s_mov_b64 s[0:1], s[10:11]
	s_mov_b32 s12, s70
	s_cbranch_scc0 .LBB0_1414
	s_nop 0
	s_nop 0
	s_nop 0
	s_nop 0
	s_nop 0
	s_nop 0
	s_nop 0
	s_nop 0
	s_nop 0
	s_nop 0
	s_nop 0
	s_nop 0
	s_and_b64 vcc, exec, s[42:43]
	s_cbranch_vccz .LBB0_1417
	s_barrier
